# v10 + FoX cross-item prefetch: next item's first 3 K/V/key-bias tiles issued by LDS-DMA at the top of the current item's epilogue
# baseline (speedup 1.0000x reference)
.LBB0_710:
	v_readlane_b32 s66, v255, 29
	s_mov_b32 s98, 0
	s_mov_b32 s9, 0
	s_mov_b32 s36, 0
	v_readlane_b32 s67, v255, 30
	s_mov_b64 s[54:55], 0x100
	s_branch .LBB0_713
.LBB0_711:
	s_add_i32 s99, s36, 1
	s_mul_i32 s99, s99, s28
	s_cmpk_lt_i32 s99, 0x400
	s_cbranch_scc0 .Lfxp_none
	s_cmp_lg_u32 s28, 0x100
	s_cbranch_scc1 .Lfxp_none
	s_mov_b64 s[100:101], 0x1000000
	v_lshl_add_u64 v[154:155], v[104:105], 0, s[100:101]
	v_lshl_add_u64 v[156:157], v[102:103], 0, s[100:101]
	v_lshl_add_u64 v[158:159], v[106:107], 0, s[100:101]
	s_mov_b64 s[100:101], 0x10000
	v_lshl_add_u64 v[160:161], v[108:109], 0, s[100:101]
	s_add_i32 m0, s39, 0x0
	s_nop 0
	global_load_lds_dwordx4 v[154:155], off
	s_add_i32 m0, s39, 0x2000
	s_nop 0
	global_load_lds_dwordx4 v[156:157], off
	s_cmp_lg_u64 s[4:5], 0
	s_cbranch_scc1 .Lfxp_c0
	s_add_i32 m0, s39, 0x4000
	s_nop 0
	global_load_lds_dwordx4 v[158:159], off
.Lfxp_c0:
	s_add_i32 m0, s40, 0x5400
	s_nop 0
	global_load_lds_dword v[160:161], off
	v_lshl_add_u64 v[154:155], v[154:155], 0, s[0:1]
	v_lshl_add_u64 v[156:157], v[156:157], 0, s[0:1]
	v_lshl_add_u64 v[158:159], v[158:159], 0, s[0:1]
	v_lshl_add_u64 v[160:161], v[160:161], 0, s[54:55]
	s_add_i32 m0, s39, 0x5c00
	s_nop 0
	global_load_lds_dwordx4 v[154:155], off
	s_add_i32 m0, s39, 0x7c00
	s_nop 0
	global_load_lds_dwordx4 v[156:157], off
	s_cmp_lg_u64 s[4:5], 0
	s_cbranch_scc1 .Lfxp_c5c00
	s_add_i32 m0, s39, 0x9c00
	s_nop 0
	global_load_lds_dwordx4 v[158:159], off
.Lfxp_c5c00:
	s_add_i32 m0, s40, 0xb000
	s_nop 0
	global_load_lds_dword v[160:161], off
	v_lshl_add_u64 v[154:155], v[154:155], 0, s[0:1]
	v_lshl_add_u64 v[156:157], v[156:157], 0, s[0:1]
	v_lshl_add_u64 v[158:159], v[158:159], 0, s[0:1]
	v_lshl_add_u64 v[160:161], v[160:161], 0, s[54:55]
	s_add_i32 m0, s39, 0xb800
	s_nop 0
	global_load_lds_dwordx4 v[154:155], off
	s_add_i32 m0, s39, 0xd800
	s_nop 0
	global_load_lds_dwordx4 v[156:157], off
	s_cmp_lg_u64 s[4:5], 0
	s_cbranch_scc1 .Lfxp_cb800
	s_add_i32 m0, s39, 0xf800
	s_nop 0
	global_load_lds_dwordx4 v[158:159], off
.Lfxp_cb800:
	s_add_i32 m0, s40, 0x10c00
	s_nop 0
	global_load_lds_dword v[160:161], off
	s_mov_b32 s98, 1

.LBB0_736:
	s_cmp_eq_u32 s98, 1
	s_cbranch_scc0 .Lfxp_orig
	v_lshlrev_b32_e32 v0, 3, v6
	v_cmp_gt_i32_e32 vcc, 8, v6
	s_lshl_b32 s39, s15, 10
	s_add_i32 s12, s39, 0
	v_cndmask_b32_e32 v6, 0, v0, vcc
	v_lshlrev_b32_e32 v0, 3, v2
	v_cmp_gt_i32_e32 vcc, 8, v2
	v_ashrrev_i32_e32 v7, 31, v6
	s_nop 0
	v_cndmask_b32_e32 v2, 0, v0, vcc
	v_ashrrev_i32_e32 v3, 31, v2
	v_lshl_add_u64 v[104:105], v[2:3], 1, v[4:5]
	v_lshl_add_u64 v[102:103], v[6:7], 1, v[8:9]
	v_lshlrev_b32_e32 v0, 3, v10
	v_cmp_gt_i32_e32 vcc, 8, v10
	s_cmp_lt_i32 s15, 5
	s_cselect_b64 s[4:5], -1, 0
	v_cndmask_b32_e32 v2, 0, v0, vcc
	v_ashrrev_i32_e32 v3, 31, v2
	v_lshl_add_u64 v[106:107], v[2:3], 1, v[12:13]
	s_ashr_i32 s9, s8, 31
	s_lshl_b64 s[6:7], s[8:9], 13
	v_readlane_b32 s9, v254, 21
	s_add_u32 s26, s9, s6
	v_readlane_b32 s9, v254, 22
	s_addc_u32 s27, s9, s7
	s_lshl_b32 s40, s15, 8
	s_add_i32 s17, s40, 0
	v_lshlrev_b32_e32 v0, 2, v16
	s_lshl_b32 s9, s37, 2
	s_add_i32 s9, s9, 4
	v_cndmask_b32_e64 v2, 0, 1, s[4:5]
	v_lshl_add_u64 v[108:109], s[26:27], 0, v[0:1]
	s_nop 0
	v_cmp_ne_u32_e64 s[4:5], 1, v2
	s_mov_b64 s[12:13], 0x200
	s_mov_b32 s98, 0
	s_branch .LBB0_746
